# k20 + G1 GEMM main loop: per-cluster s_setprio flips removed, one static s_setprio 1 for waves 4-7 (lever 4 on the SwiGLU GEMM)
# speedup vs baseline: 1.0022x; 1.0022x over previous
.LBB0_326:
	v_readlane_b32 s31, v253, 16
	s_nop 0
	s_cmp_ge_u32 s31, 4
	s_cbranch_scc0 .Lg1_prio_done
	s_setprio 1
.Lg1_prio_done:
	s_add_u32 s18, s16, 0xfffc0080
	s_addc_u32 s19, s17, -1
	s_add_i32 s44, 0, 0x10000
	s_cmp_eq_u32 s43, 12
	s_cselect_b32 s21, s9, s19
	s_cselect_b32 s20, s36, s18
	s_cselect_b32 s19, s3, s42
	s_cselect_b32 s18, s40, s41
	s_add_i32 s46, 0, 0x14000
	v_add_u32_e32 v156, s44, v146
	v_add_u32_e32 v172, s46, v146
	ds_read_b128 v[140:143], v156
	ds_read_b128 v[148:151], v156 offset:1024
	ds_read_b128 v[152:155], v156 offset:2048
	ds_read_b128 v[156:159], v156 offset:3072
	ds_read_b128 v[160:163], v172
	ds_read_b128 v[164:167], v172 offset:1024
	ds_read_b128 v[168:171], v172 offset:2048
	ds_read_b128 v[172:175], v172 offset:3072
	v_lshl_add_u64 v[196:197], s[16:17], 0, v[136:137]
	s_add_i32 m0, s26, 0xc000
	ds_read_b128 v[176:179], v147
	ds_read_b128 v[180:183], v147 offset:1024
	ds_read_b128 v[184:187], v147 offset:2048
	ds_read_b128 v[188:191], v147 offset:3072
	ds_read_b128 v[192:195], v147 offset:4096
	ds_read_b128 v[206:209], v147 offset:5120
	ds_read_b128 v[210:213], v147 offset:6144
	ds_read_b128 v[214:217], v147 offset:7168
	global_load_lds_dwordx4 v[196:197], off
	v_lshl_add_u64 v[196:197], s[16:17], 0, v[138:139]
	s_add_i32 m0, s26, 0xe000
	s_nop 0
	global_load_lds_dwordx4 v[196:197], off
	s_waitcnt vmcnt(8)
	s_waitcnt lgkmcnt(0)
	s_barrier
	s_nop 0
	s_waitcnt lgkmcnt(0)
	v_mfma_f32_16x16x32_bf16 v[126:129], v[140:143], v[176:179], v[126:129]
	v_mfma_f32_16x16x32_bf16 v[118:121], v[152:155], v[176:179], v[118:121]
	v_mfma_f32_16x16x32_bf16 v[110:113], v[140:143], v[184:187], v[110:113]
	v_mfma_f32_16x16x32_bf16 v[102:105], v[152:155], v[184:187], v[102:105]
	v_mfma_f32_16x16x32_bf16 v[94:97], v[140:143], v[192:195], v[94:97]
	v_mfma_f32_16x16x32_bf16 v[86:89], v[152:155], v[192:195], v[86:89]
	v_mfma_f32_16x16x32_bf16 v[78:81], v[140:143], v[210:213], v[78:81]
	v_mfma_f32_16x16x32_bf16 v[70:73], v[152:155], v[210:213], v[70:73]
	v_mfma_f32_16x16x32_bf16 v[126:129], v[148:151], v[180:183], v[126:129]
	v_mfma_f32_16x16x32_bf16 v[118:121], v[156:159], v[180:183], v[118:121]
	v_mfma_f32_16x16x32_bf16 v[110:113], v[148:151], v[188:191], v[110:113]
	v_mfma_f32_16x16x32_bf16 v[102:105], v[156:159], v[188:191], v[102:105]
	v_mfma_f32_16x16x32_bf16 v[94:97], v[148:151], v[206:209], v[94:97]
	v_mfma_f32_16x16x32_bf16 v[86:89], v[156:159], v[206:209], v[86:89]
	v_mfma_f32_16x16x32_bf16 v[78:81], v[148:151], v[214:217], v[78:81]
	v_mfma_f32_16x16x32_bf16 v[70:73], v[156:159], v[214:217], v[70:73]
	s_nop 0
	s_nop 0
	v_mfma_f32_16x16x32_bf16 v[122:125], v[160:163], v[176:179], v[122:125]
	v_mfma_f32_16x16x32_bf16 v[114:117], v[168:171], v[176:179], v[114:117]
	v_mfma_f32_16x16x32_bf16 v[106:109], v[160:163], v[184:187], v[106:109]
	v_mfma_f32_16x16x32_bf16 v[98:101], v[168:171], v[184:187], v[98:101]
	v_mfma_f32_16x16x32_bf16 v[90:93], v[160:163], v[192:195], v[90:93]
	v_mfma_f32_16x16x32_bf16 v[82:85], v[168:171], v[192:195], v[82:85]
	v_mfma_f32_16x16x32_bf16 v[74:77], v[160:163], v[210:213], v[74:77]
	v_mfma_f32_16x16x32_bf16 v[66:69], v[168:171], v[210:213], v[66:69]
	v_mfma_f32_16x16x32_bf16 v[122:125], v[164:167], v[180:183], v[122:125]
	v_mfma_f32_16x16x32_bf16 v[114:117], v[172:175], v[180:183], v[114:117]
	v_mfma_f32_16x16x32_bf16 v[106:109], v[164:167], v[188:191], v[106:109]
	v_mfma_f32_16x16x32_bf16 v[98:101], v[172:175], v[188:191], v[98:101]
	v_mfma_f32_16x16x32_bf16 v[90:93], v[164:167], v[206:209], v[90:93]
	v_mfma_f32_16x16x32_bf16 v[82:85], v[172:175], v[206:209], v[82:85]
	v_mfma_f32_16x16x32_bf16 v[74:77], v[164:167], v[214:217], v[74:77]
	v_mfma_f32_16x16x32_bf16 v[66:69], v[172:175], v[214:217], v[66:69]
	s_nop 0
	s_barrier
	s_add_i32 s44, s44, s63
	v_lshl_add_u64 v[196:197], s[18:19], 0, v[0:1]
	s_mov_b32 m0, s44
	ds_read_b128 v[176:179], v147 offset:16384
	ds_read_b128 v[180:183], v147 offset:17408
	ds_read_b128 v[184:187], v147 offset:18432
	ds_read_b128 v[188:191], v147 offset:19456
	ds_read_b128 v[192:195], v147 offset:20480
	ds_read_b128 v[206:209], v147 offset:21504
	ds_read_b128 v[210:213], v147 offset:22528
	ds_read_b128 v[214:217], v147 offset:23552
	global_load_lds_dwordx4 v[196:197], off
	s_add_i32 m0, s44, 0x2000
	s_add_u32 s44, s18, 0x40000
	v_lshl_add_u64 v[218:219], s[18:19], 0, v[130:131]
	s_addc_u32 s45, s19, 0
	s_add_i32 s46, s46, s63
	global_load_lds_dwordx4 v[218:219], off
	v_lshl_add_u64 v[220:221], s[44:45], 0, v[0:1]
	s_mov_b32 m0, s46
	v_lshl_add_u64 v[222:223], s[20:21], 0, v[132:133]
	global_load_lds_dwordx4 v[220:221], off
	v_lshl_add_u64 v[220:221], s[44:45], 0, v[130:131]
	s_add_i32 m0, s46, 0x2000
	s_nop 0
	global_load_lds_dwordx4 v[220:221], off
	v_lshl_add_u64 v[220:221], s[20:21], 0, v[134:135]
	s_mov_b32 m0, s26
	s_nop 0
	global_load_lds_dwordx4 v[220:221], off
	s_mov_b32 m0, s27
	s_nop 0
	global_load_lds_dwordx4 v[222:223], off
	s_waitcnt vmcnt(8)
	s_waitcnt lgkmcnt(0)
	s_barrier
	s_nop 0
	s_waitcnt lgkmcnt(0)
	v_mfma_f32_16x16x32_bf16 v[62:65], v[140:143], v[176:179], v[62:65]
	v_mfma_f32_16x16x32_bf16 v[54:57], v[152:155], v[176:179], v[54:57]
	v_mfma_f32_16x16x32_bf16 v[46:49], v[140:143], v[184:187], v[46:49]
	v_mfma_f32_16x16x32_bf16 v[38:41], v[152:155], v[184:187], v[38:41]
	v_mfma_f32_16x16x32_bf16 v[30:33], v[140:143], v[192:195], v[30:33]
	v_mfma_f32_16x16x32_bf16 v[22:25], v[152:155], v[192:195], v[22:25]
	v_mfma_f32_16x16x32_bf16 v[14:17], v[140:143], v[210:213], v[14:17]
	v_mfma_f32_16x16x32_bf16 v[6:9], v[152:155], v[210:213], v[6:9]
	v_mfma_f32_16x16x32_bf16 v[62:65], v[148:151], v[180:183], v[62:65]
	v_mfma_f32_16x16x32_bf16 v[54:57], v[156:159], v[180:183], v[54:57]
	v_mfma_f32_16x16x32_bf16 v[46:49], v[148:151], v[188:191], v[46:49]
	v_mfma_f32_16x16x32_bf16 v[38:41], v[156:159], v[188:191], v[38:41]
	v_mfma_f32_16x16x32_bf16 v[30:33], v[148:151], v[206:209], v[30:33]
	v_mfma_f32_16x16x32_bf16 v[22:25], v[156:159], v[206:209], v[22:25]
	v_mfma_f32_16x16x32_bf16 v[14:17], v[148:151], v[214:217], v[14:17]
	v_mfma_f32_16x16x32_bf16 v[6:9], v[156:159], v[214:217], v[6:9]
	s_nop 0
	s_nop 0
	v_mfma_f32_16x16x32_bf16 v[58:61], v[160:163], v[176:179], v[58:61]
	v_mfma_f32_16x16x32_bf16 v[50:53], v[168:171], v[176:179], v[50:53]
	v_mfma_f32_16x16x32_bf16 v[42:45], v[160:163], v[184:187], v[42:45]
	v_mfma_f32_16x16x32_bf16 v[34:37], v[168:171], v[184:187], v[34:37]
	v_mfma_f32_16x16x32_bf16 v[26:29], v[160:163], v[192:195], v[26:29]
	v_mfma_f32_16x16x32_bf16 v[18:21], v[168:171], v[192:195], v[18:21]
	v_mfma_f32_16x16x32_bf16 v[10:13], v[160:163], v[210:213], v[10:13]
	v_mfma_f32_16x16x32_bf16 v[2:5], v[168:171], v[210:213], v[2:5]
	v_mfma_f32_16x16x32_bf16 v[58:61], v[164:167], v[180:183], v[58:61]
	v_mfma_f32_16x16x32_bf16 v[50:53], v[172:175], v[180:183], v[50:53]
	v_mfma_f32_16x16x32_bf16 v[42:45], v[164:167], v[188:191], v[42:45]
	v_mfma_f32_16x16x32_bf16 v[34:37], v[172:175], v[188:191], v[34:37]
	v_mfma_f32_16x16x32_bf16 v[26:29], v[164:167], v[206:209], v[26:29]
	v_mfma_f32_16x16x32_bf16 v[18:21], v[172:175], v[206:209], v[18:21]
	v_mfma_f32_16x16x32_bf16 v[10:13], v[164:167], v[214:217], v[10:13]
	v_mfma_f32_16x16x32_bf16 v[2:5], v[172:175], v[214:217], v[2:5]
	s_nop 0
	s_barrier
	s_add_i32 s44, 0, 0x18000
	s_add_i32 s45, 0, 0x1c000
	v_add_u32_e32 v156, s44, v146
	v_add_u32_e32 v172, s45, v146
	ds_read_b128 v[140:143], v156
	ds_read_b128 v[148:151], v156 offset:1024
	ds_read_b128 v[152:155], v156 offset:2048
	ds_read_b128 v[156:159], v156 offset:3072
	ds_read_b128 v[160:163], v172
	ds_read_b128 v[164:167], v172 offset:1024
	ds_read_b128 v[168:171], v172 offset:2048
	ds_read_b128 v[172:175], v172 offset:3072
	s_add_u32 s20, s20, 0x40000
	s_addc_u32 s21, s21, 0
	s_mov_b32 m0, s28
	v_lshl_add_u64 v[224:225], s[20:21], 0, v[134:135]
	ds_read_b128 v[176:179], v147 offset:32768
	ds_read_b128 v[180:183], v147 offset:33792
	ds_read_b128 v[184:187], v147 offset:34816
	ds_read_b128 v[188:191], v147 offset:35840
	ds_read_b128 v[192:195], v147 offset:36864
	ds_read_b128 v[206:209], v147 offset:37888
	ds_read_b128 v[210:213], v147 offset:38912
	ds_read_b128 v[214:217], v147 offset:39936
	global_load_lds_dwordx4 v[224:225], off
	v_lshl_add_u64 v[224:225], s[20:21], 0, v[132:133]
	s_mov_b32 m0, s29
	s_nop 0
	global_load_lds_dwordx4 v[224:225], off
	s_waitcnt vmcnt(8)
	s_waitcnt lgkmcnt(0)
	s_barrier
	s_nop 0
	s_waitcnt lgkmcnt(0)
	v_mfma_f32_16x16x32_bf16 v[126:129], v[140:143], v[176:179], v[126:129]
	v_mfma_f32_16x16x32_bf16 v[118:121], v[152:155], v[176:179], v[118:121]
	v_mfma_f32_16x16x32_bf16 v[110:113], v[140:143], v[184:187], v[110:113]
	v_mfma_f32_16x16x32_bf16 v[102:105], v[152:155], v[184:187], v[102:105]
	v_mfma_f32_16x16x32_bf16 v[94:97], v[140:143], v[192:195], v[94:97]
	v_mfma_f32_16x16x32_bf16 v[86:89], v[152:155], v[192:195], v[86:89]
	v_mfma_f32_16x16x32_bf16 v[78:81], v[140:143], v[210:213], v[78:81]
	v_mfma_f32_16x16x32_bf16 v[70:73], v[152:155], v[210:213], v[70:73]
	v_mfma_f32_16x16x32_bf16 v[126:129], v[148:151], v[180:183], v[126:129]
	v_mfma_f32_16x16x32_bf16 v[118:121], v[156:159], v[180:183], v[118:121]
	v_mfma_f32_16x16x32_bf16 v[110:113], v[148:151], v[188:191], v[110:113]
	v_mfma_f32_16x16x32_bf16 v[102:105], v[156:159], v[188:191], v[102:105]
	v_mfma_f32_16x16x32_bf16 v[94:97], v[148:151], v[206:209], v[94:97]
	v_mfma_f32_16x16x32_bf16 v[86:89], v[156:159], v[206:209], v[86:89]
	v_mfma_f32_16x16x32_bf16 v[78:81], v[148:151], v[214:217], v[78:81]
	v_mfma_f32_16x16x32_bf16 v[70:73], v[156:159], v[214:217], v[70:73]
	s_nop 0
	s_nop 0
	v_mfma_f32_16x16x32_bf16 v[122:125], v[160:163], v[176:179], v[122:125]
	v_mfma_f32_16x16x32_bf16 v[114:117], v[168:171], v[176:179], v[114:117]
	v_mfma_f32_16x16x32_bf16 v[106:109], v[160:163], v[184:187], v[106:109]
	v_mfma_f32_16x16x32_bf16 v[98:101], v[168:171], v[184:187], v[98:101]
	v_mfma_f32_16x16x32_bf16 v[90:93], v[160:163], v[192:195], v[90:93]
	v_mfma_f32_16x16x32_bf16 v[82:85], v[168:171], v[192:195], v[82:85]
	v_mfma_f32_16x16x32_bf16 v[74:77], v[160:163], v[210:213], v[74:77]
	v_mfma_f32_16x16x32_bf16 v[66:69], v[168:171], v[210:213], v[66:69]
	v_mfma_f32_16x16x32_bf16 v[122:125], v[164:167], v[180:183], v[122:125]
	v_mfma_f32_16x16x32_bf16 v[114:117], v[172:175], v[180:183], v[114:117]
	v_mfma_f32_16x16x32_bf16 v[106:109], v[164:167], v[188:191], v[106:109]
	v_mfma_f32_16x16x32_bf16 v[98:101], v[172:175], v[188:191], v[98:101]
	v_mfma_f32_16x16x32_bf16 v[90:93], v[164:167], v[206:209], v[90:93]
	v_mfma_f32_16x16x32_bf16 v[82:85], v[172:175], v[206:209], v[82:85]
	v_mfma_f32_16x16x32_bf16 v[74:77], v[164:167], v[214:217], v[74:77]
	v_mfma_f32_16x16x32_bf16 v[66:69], v[172:175], v[214:217], v[66:69]
	s_nop 0
	s_barrier
	s_add_i32 s20, s44, s63
	v_lshl_add_u64 v[196:197], v[196:197], 0, s[48:49]
	s_mov_b32 m0, s20
	ds_read_b128 v[176:179], v147 offset:49152
	ds_read_b128 v[180:183], v147 offset:50176
	ds_read_b128 v[184:187], v147 offset:51200
	ds_read_b128 v[188:191], v147 offset:52224
	ds_read_b128 v[192:195], v147 offset:53248
	ds_read_b128 v[206:209], v147 offset:54272
	ds_read_b128 v[210:213], v147 offset:55296
	ds_read_b128 v[214:217], v147 offset:56320
	global_load_lds_dwordx4 v[196:197], off
	s_add_i32 m0, s20, 0x2000
	s_add_u32 s18, s18, 0x40080
	v_lshl_add_u64 v[196:197], v[218:219], 0, s[48:49]
	s_addc_u32 s19, s19, 0
	s_add_i32 s20, s45, s63
	global_load_lds_dwordx4 v[196:197], off
	v_lshl_add_u64 v[196:197], s[18:19], 0, v[0:1]
	s_mov_b32 m0, s20
	s_nop 0
	global_load_lds_dwordx4 v[196:197], off
	v_lshl_add_u64 v[196:197], s[18:19], 0, v[130:131]
	s_add_i32 m0, s20, 0x2000
	s_nop 0
	global_load_lds_dwordx4 v[196:197], off
	v_lshl_add_u64 v[196:197], v[220:221], 0, s[48:49]
	s_mov_b32 m0, s30
	s_nop 0
	global_load_lds_dwordx4 v[196:197], off
	v_lshl_add_u64 v[196:197], v[222:223], 0, s[48:49]
	s_mov_b32 m0, s34
	s_nop 0
	global_load_lds_dwordx4 v[196:197], off
	s_waitcnt vmcnt(8)
	s_waitcnt lgkmcnt(0)
	s_barrier
	s_nop 0
	s_waitcnt lgkmcnt(0)
	v_mfma_f32_16x16x32_bf16 v[62:65], v[140:143], v[176:179], v[62:65]
	v_mfma_f32_16x16x32_bf16 v[54:57], v[152:155], v[176:179], v[54:57]
	v_mfma_f32_16x16x32_bf16 v[46:49], v[140:143], v[184:187], v[46:49]
	v_mfma_f32_16x16x32_bf16 v[38:41], v[152:155], v[184:187], v[38:41]
	v_mfma_f32_16x16x32_bf16 v[30:33], v[140:143], v[192:195], v[30:33]
	v_mfma_f32_16x16x32_bf16 v[22:25], v[152:155], v[192:195], v[22:25]
	v_mfma_f32_16x16x32_bf16 v[14:17], v[140:143], v[210:213], v[14:17]
	v_mfma_f32_16x16x32_bf16 v[6:9], v[152:155], v[210:213], v[6:9]
	v_mfma_f32_16x16x32_bf16 v[62:65], v[148:151], v[180:183], v[62:65]
	v_mfma_f32_16x16x32_bf16 v[54:57], v[156:159], v[180:183], v[54:57]
	v_mfma_f32_16x16x32_bf16 v[46:49], v[148:151], v[188:191], v[46:49]
	v_mfma_f32_16x16x32_bf16 v[38:41], v[156:159], v[188:191], v[38:41]
	v_mfma_f32_16x16x32_bf16 v[30:33], v[148:151], v[206:209], v[30:33]
	v_mfma_f32_16x16x32_bf16 v[22:25], v[156:159], v[206:209], v[22:25]
	v_mfma_f32_16x16x32_bf16 v[14:17], v[148:151], v[214:217], v[14:17]
	v_mfma_f32_16x16x32_bf16 v[6:9], v[156:159], v[214:217], v[6:9]
	s_nop 0
	s_nop 0
	v_mfma_f32_16x16x32_bf16 v[58:61], v[160:163], v[176:179], v[58:61]
	v_mfma_f32_16x16x32_bf16 v[50:53], v[168:171], v[176:179], v[50:53]
	v_mfma_f32_16x16x32_bf16 v[42:45], v[160:163], v[184:187], v[42:45]
	v_mfma_f32_16x16x32_bf16 v[34:37], v[168:171], v[184:187], v[34:37]
	v_mfma_f32_16x16x32_bf16 v[26:29], v[160:163], v[192:195], v[26:29]
	v_mfma_f32_16x16x32_bf16 v[18:21], v[168:171], v[192:195], v[18:21]
	v_mfma_f32_16x16x32_bf16 v[10:13], v[160:163], v[210:213], v[10:13]
	v_mfma_f32_16x16x32_bf16 v[2:5], v[168:171], v[210:213], v[2:5]
	v_mfma_f32_16x16x32_bf16 v[58:61], v[164:167], v[180:183], v[58:61]
	v_mfma_f32_16x16x32_bf16 v[50:53], v[172:175], v[180:183], v[50:53]
	v_mfma_f32_16x16x32_bf16 v[42:45], v[164:167], v[188:191], v[42:45]
	v_mfma_f32_16x16x32_bf16 v[34:37], v[172:175], v[188:191], v[34:37]
	v_mfma_f32_16x16x32_bf16 v[26:29], v[164:167], v[206:209], v[26:29]
	v_mfma_f32_16x16x32_bf16 v[18:21], v[172:175], v[206:209], v[18:21]
	v_mfma_f32_16x16x32_bf16 v[10:13], v[164:167], v[214:217], v[10:13]
	v_mfma_f32_16x16x32_bf16 v[2:5], v[172:175], v[214:217], v[2:5]
	s_nop 0
	s_barrier
	s_add_i32 s43, s43, 2
	s_add_u32 s16, s16, 0x100
	s_addc_u32 s17, s17, 0
	s_add_u32 s41, s41, 0x100
	s_addc_u32 s42, s42, 0
	s_cmp_gt_u32 s43, 13
	s_cbranch_scc0 .LBB0_326
	v_readlane_b32 s16, v253, 25
	v_readlane_b32 s17, v253, 26
	s_and_b64 vcc, exec, s[16:17]
	s_cbranch_vccz .LBB0_329
	s_barrier
.LBB0_329:
	s_setprio 0
	v_mul_f32_e32 v149, 0xbfb8aa3b, v126
	v_exp_f32_e32 v149, v149
	s_mov_b32 s3, s67
	v_mov_b32_e32 v140, v144
	s_mov_b32 s9, s66
	v_add_f32_e32 v149, 1.0, v149
	v_rcp_f32_e32 v152, v149
	v_mul_f32_e32 v149, 0xbfb8aa3b, v127
	v_exp_f32_e32 v149, v149
	v_mov_b32_e32 v141, v145
	s_lshl_b32 s14, s14, 8
	v_add_f32_e32 v149, 1.0, v149
	v_rcp_f32_e32 v153, v149
	s_lshl_b32 s9, s9, 6
	s_add_i32 s9, s9, s14
	v_add_u32_e32 v148, s9, v140
	v_pk_mul_f32 v[126:127], v[126:127], v[152:153]
	s_lshl_b32 s9, s15, 7
	v_pk_mul_f32 v[122:123], v[126:127], v[122:123]
	s_lshl_b32 s3, s3, 5
	v_cvt_pk_bf16_f32 v122, v122, v123
	v_mul_f32_e32 v123, 0xbfb8aa3b, v128
	v_exp_f32_e32 v123, v123
	s_add_i32 s3, s3, s9
	v_lshl_add_u32 v142, v141, 3, s3
	v_ashrrev_i32_e32 v143, 31, v142
	v_add_f32_e32 v123, 1.0, v123
	v_rcp_f32_e32 v126, v123
	v_mul_f32_e32 v123, 0xbfb8aa3b, v129
	v_exp_f32_e32 v123, v123
	v_mov_b64_e32 v[140:141], s[0:1]
	s_movk_i32 s3, 0x1600
	v_mad_i64_i32 v[150:151], s[14:15], v148, s3, v[140:141]
	v_add_f32_e32 v123, 1.0, v123
	v_rcp_f32_e32 v127, v123
	v_lshlrev_b64 v[142:143], 1, v[142:143]
	v_lshl_add_u64 v[150:151], v[150:151], 0, v[142:143]
	s_andn2_b64 vcc, exec, s[6:7]
	v_pk_mul_f32 v[126:127], v[128:129], v[126:127]
	s_nop 0
	v_pk_mul_f32 v[124:125], v[126:127], v[124:125]
	s_nop 0
	v_cvt_pk_bf16_f32 v123, v124, v125
	v_mul_f32_e32 v124, 0xbfb8aa3b, v118
	v_mul_f32_e32 v125, 0xbfb8aa3b, v119
	v_exp_f32_e32 v124, v124
	v_exp_f32_e32 v125, v125
	v_add_f32_e32 v124, 1.0, v124
	v_add_f32_e32 v125, 1.0, v125
	v_rcp_f32_e32 v124, v124
	v_rcp_f32_e32 v125, v125
	s_nop 0
	v_pk_mul_f32 v[118:119], v[118:119], v[124:125]
	s_nop 0
	v_pk_mul_f32 v[114:115], v[118:119], v[114:115]
	s_nop 0
	v_cvt_pk_bf16_f32 v124, v114, v115
	v_mul_f32_e32 v114, 0xbfb8aa3b, v120
	v_mul_f32_e32 v115, 0xbfb8aa3b, v121
	v_exp_f32_e32 v114, v114
	v_exp_f32_e32 v115, v115
	v_add_f32_e32 v114, 1.0, v114
	v_add_f32_e32 v115, 1.0, v115
	v_rcp_f32_e32 v114, v114
	v_rcp_f32_e32 v115, v115
	s_nop 0
	v_pk_mul_f32 v[114:115], v[120:121], v[114:115]
	s_nop 0
	v_pk_mul_f32 v[114:115], v[114:115], v[116:117]
	v_mul_f32_e32 v116, 0xbfb8aa3b, v110
	v_mul_f32_e32 v117, 0xbfb8aa3b, v111
	v_exp_f32_e32 v116, v116
	v_exp_f32_e32 v117, v117
	v_cvt_pk_bf16_f32 v125, v114, v115
	v_add_u32_e32 v114, 16, v148
	v_add_f32_e32 v116, 1.0, v116
	v_add_f32_e32 v117, 1.0, v117
	v_rcp_f32_e32 v116, v116
	v_rcp_f32_e32 v117, v117
	v_mad_i64_i32 v[114:115], s[14:15], v114, s3, v[140:141]
	v_lshl_add_u64 v[114:115], v[114:115], 0, v[142:143]
	v_pk_mul_f32 v[110:111], v[110:111], v[116:117]
	global_store_dwordx4 v[150:151], v[122:125], off
	v_pk_mul_f32 v[106:107], v[110:111], v[106:107]
	s_nop 0
	v_cvt_pk_bf16_f32 v106, v106, v107
	v_mul_f32_e32 v107, 0xbfb8aa3b, v112
	v_exp_f32_e32 v107, v107
	s_nop 0
	v_add_f32_e32 v107, 1.0, v107
	v_rcp_f32_e32 v110, v107
	v_mul_f32_e32 v107, 0xbfb8aa3b, v113
	v_exp_f32_e32 v107, v107
	s_nop 0
	v_add_f32_e32 v107, 1.0, v107
	v_rcp_f32_e32 v111, v107
	s_nop 0
	v_pk_mul_f32 v[110:111], v[112:113], v[110:111]
	s_nop 0
	v_pk_mul_f32 v[108:109], v[110:111], v[108:109]
	s_nop 0
	v_cvt_pk_bf16_f32 v107, v108, v109
	v_mul_f32_e32 v108, 0xbfb8aa3b, v102
	v_mul_f32_e32 v109, 0xbfb8aa3b, v103
	v_exp_f32_e32 v108, v108
	v_exp_f32_e32 v109, v109
	v_add_f32_e32 v108, 1.0, v108
	v_add_f32_e32 v109, 1.0, v109
	v_rcp_f32_e32 v108, v108
	v_rcp_f32_e32 v109, v109
	s_nop 0
	v_pk_mul_f32 v[102:103], v[102:103], v[108:109]
	s_nop 0
	v_pk_mul_f32 v[98:99], v[102:103], v[98:99]
	s_nop 0
	v_cvt_pk_bf16_f32 v108, v98, v99
	v_mul_f32_e32 v98, 0xbfb8aa3b, v104
	v_mul_f32_e32 v99, 0xbfb8aa3b, v105
	v_exp_f32_e32 v98, v98
	v_exp_f32_e32 v99, v99
	v_add_f32_e32 v98, 1.0, v98
	v_add_f32_e32 v99, 1.0, v99
	v_rcp_f32_e32 v98, v98
	v_rcp_f32_e32 v99, v99
	s_nop 0
	v_pk_mul_f32 v[98:99], v[104:105], v[98:99]
	s_nop 0
	v_pk_mul_f32 v[98:99], v[98:99], v[100:101]
	v_mul_f32_e32 v100, 0xbfb8aa3b, v94
	v_mul_f32_e32 v101, 0xbfb8aa3b, v95
	v_exp_f32_e32 v100, v100
	v_exp_f32_e32 v101, v101
	v_cvt_pk_bf16_f32 v109, v98, v99
	v_add_u32_e32 v98, 32, v148
	v_add_f32_e32 v100, 1.0, v100
	v_add_f32_e32 v101, 1.0, v101
	v_rcp_f32_e32 v100, v100
	v_rcp_f32_e32 v101, v101
	v_mad_i64_i32 v[98:99], s[14:15], v98, s3, v[140:141]
	v_lshl_add_u64 v[98:99], v[98:99], 0, v[142:143]
	v_pk_mul_f32 v[94:95], v[94:95], v[100:101]
	global_store_dwordx4 v[114:115], v[106:109], off
	v_pk_mul_f32 v[90:91], v[94:95], v[90:91]
	s_nop 0
	v_cvt_pk_bf16_f32 v90, v90, v91
	v_mul_f32_e32 v91, 0xbfb8aa3b, v96
	v_exp_f32_e32 v91, v91
	s_nop 0
	v_add_f32_e32 v91, 1.0, v91
	v_rcp_f32_e32 v94, v91
	v_mul_f32_e32 v91, 0xbfb8aa3b, v97
	v_exp_f32_e32 v91, v91
	s_nop 0
	v_add_f32_e32 v91, 1.0, v91
	v_rcp_f32_e32 v95, v91
	s_nop 0
	v_pk_mul_f32 v[94:95], v[96:97], v[94:95]
	s_nop 0
	v_pk_mul_f32 v[92:93], v[94:95], v[92:93]
	s_nop 0
	v_cvt_pk_bf16_f32 v91, v92, v93
	v_mul_f32_e32 v92, 0xbfb8aa3b, v86
	v_mul_f32_e32 v93, 0xbfb8aa3b, v87
	v_exp_f32_e32 v92, v92
	v_exp_f32_e32 v93, v93
	v_add_f32_e32 v92, 1.0, v92
	v_add_f32_e32 v93, 1.0, v93
	v_rcp_f32_e32 v92, v92
	v_rcp_f32_e32 v93, v93
	s_nop 0
	v_pk_mul_f32 v[86:87], v[86:87], v[92:93]
	s_nop 0
	v_pk_mul_f32 v[82:83], v[86:87], v[82:83]
	s_nop 0
	v_cvt_pk_bf16_f32 v92, v82, v83
	v_mul_f32_e32 v82, 0xbfb8aa3b, v88
	v_mul_f32_e32 v83, 0xbfb8aa3b, v89
	v_exp_f32_e32 v82, v82
	v_exp_f32_e32 v83, v83
	v_add_f32_e32 v82, 1.0, v82
	v_add_f32_e32 v83, 1.0, v83
	v_rcp_f32_e32 v82, v82
	v_rcp_f32_e32 v83, v83
	s_nop 0
	v_pk_mul_f32 v[82:83], v[88:89], v[82:83]
	s_nop 0
	v_pk_mul_f32 v[82:83], v[82:83], v[84:85]
	v_mul_f32_e32 v84, 0xbfb8aa3b, v78
	v_mul_f32_e32 v85, 0xbfb8aa3b, v79
	v_exp_f32_e32 v84, v84
	v_exp_f32_e32 v85, v85
	v_cvt_pk_bf16_f32 v93, v82, v83
	v_add_u32_e32 v82, 48, v148
	v_add_f32_e32 v84, 1.0, v84
	v_add_f32_e32 v85, 1.0, v85
	v_rcp_f32_e32 v84, v84
	v_rcp_f32_e32 v85, v85
	v_mad_i64_i32 v[82:83], s[14:15], v82, s3, v[140:141]
	v_lshl_add_u64 v[82:83], v[82:83], 0, v[142:143]
	v_pk_mul_f32 v[78:79], v[78:79], v[84:85]
	global_store_dwordx4 v[98:99], v[90:93], off
	v_pk_mul_f32 v[74:75], v[78:79], v[74:75]
	s_nop 0
	v_cvt_pk_bf16_f32 v74, v74, v75
	v_mul_f32_e32 v75, 0xbfb8aa3b, v80
	v_exp_f32_e32 v75, v75
	s_nop 0
	v_add_f32_e32 v75, 1.0, v75
	v_rcp_f32_e32 v78, v75
	v_mul_f32_e32 v75, 0xbfb8aa3b, v81
	v_exp_f32_e32 v75, v75
	s_nop 0
	v_add_f32_e32 v75, 1.0, v75
	v_rcp_f32_e32 v79, v75
	s_nop 0
	v_pk_mul_f32 v[78:79], v[80:81], v[78:79]
	s_nop 0
	v_pk_mul_f32 v[76:77], v[78:79], v[76:77]
	s_nop 0
	v_cvt_pk_bf16_f32 v75, v76, v77
	v_mul_f32_e32 v76, 0xbfb8aa3b, v70
	v_mul_f32_e32 v77, 0xbfb8aa3b, v71
	v_exp_f32_e32 v76, v76
	v_exp_f32_e32 v77, v77
	v_add_f32_e32 v76, 1.0, v76
	v_add_f32_e32 v77, 1.0, v77
	v_rcp_f32_e32 v76, v76
	v_rcp_f32_e32 v77, v77
	s_nop 0
	v_pk_mul_f32 v[70:71], v[70:71], v[76:77]
	s_nop 0
	v_pk_mul_f32 v[66:67], v[70:71], v[66:67]
	s_nop 0
	v_cvt_pk_bf16_f32 v76, v66, v67
	v_mul_f32_e32 v66, 0xbfb8aa3b, v72
	v_mul_f32_e32 v67, 0xbfb8aa3b, v73
	v_exp_f32_e32 v66, v66
	v_exp_f32_e32 v67, v67
	v_add_f32_e32 v66, 1.0, v66
	v_add_f32_e32 v67, 1.0, v67
	v_rcp_f32_e32 v66, v66
	v_rcp_f32_e32 v67, v67
	s_nop 0
	v_pk_mul_f32 v[66:67], v[72:73], v[66:67]
	s_nop 0
	v_pk_mul_f32 v[66:67], v[66:67], v[68:69]
	v_mul_f32_e32 v68, 0xbfb8aa3b, v62
	v_mul_f32_e32 v69, 0xbfb8aa3b, v63
	v_exp_f32_e32 v68, v68
	v_exp_f32_e32 v69, v69
	v_cvt_pk_bf16_f32 v77, v66, v67
	v_add_u32_e32 v66, 0x80, v148
	v_add_f32_e32 v68, 1.0, v68
	v_add_f32_e32 v69, 1.0, v69
	v_rcp_f32_e32 v68, v68
	v_rcp_f32_e32 v69, v69
	v_mad_i64_i32 v[66:67], s[14:15], v66, s3, v[140:141]
	v_lshl_add_u64 v[66:67], v[66:67], 0, v[142:143]
	v_pk_mul_f32 v[62:63], v[62:63], v[68:69]
	global_store_dwordx4 v[82:83], v[74:77], off
	v_pk_mul_f32 v[58:59], v[62:63], v[58:59]
	s_nop 0
	v_cvt_pk_bf16_f32 v58, v58, v59
	v_mul_f32_e32 v59, 0xbfb8aa3b, v64
	v_exp_f32_e32 v59, v59
	s_nop 0
	v_add_f32_e32 v59, 1.0, v59
	v_rcp_f32_e32 v62, v59
	v_mul_f32_e32 v59, 0xbfb8aa3b, v65
	v_exp_f32_e32 v59, v59
	s_nop 0
	v_add_f32_e32 v59, 1.0, v59
	v_rcp_f32_e32 v63, v59
	s_nop 0
	v_pk_mul_f32 v[62:63], v[64:65], v[62:63]
	s_nop 0
	v_pk_mul_f32 v[60:61], v[62:63], v[60:61]
	s_nop 0
	v_cvt_pk_bf16_f32 v59, v60, v61
	v_mul_f32_e32 v60, 0xbfb8aa3b, v54
	v_mul_f32_e32 v61, 0xbfb8aa3b, v55
	v_exp_f32_e32 v60, v60
	v_exp_f32_e32 v61, v61
	v_add_f32_e32 v60, 1.0, v60
	v_add_f32_e32 v61, 1.0, v61
	v_rcp_f32_e32 v60, v60
	v_rcp_f32_e32 v61, v61
	s_nop 0
	v_pk_mul_f32 v[54:55], v[54:55], v[60:61]
	s_nop 0
	v_pk_mul_f32 v[50:51], v[54:55], v[50:51]
	s_nop 0
	v_cvt_pk_bf16_f32 v60, v50, v51
	v_mul_f32_e32 v50, 0xbfb8aa3b, v56
	v_mul_f32_e32 v51, 0xbfb8aa3b, v57
	v_exp_f32_e32 v50, v50
	v_exp_f32_e32 v51, v51
	v_add_f32_e32 v50, 1.0, v50
	v_add_f32_e32 v51, 1.0, v51
	v_rcp_f32_e32 v50, v50
	v_rcp_f32_e32 v51, v51
	s_nop 0
	v_pk_mul_f32 v[50:51], v[56:57], v[50:51]
	s_nop 0
	v_pk_mul_f32 v[50:51], v[50:51], v[52:53]
	v_mul_f32_e32 v52, 0xbfb8aa3b, v46
	v_mul_f32_e32 v53, 0xbfb8aa3b, v47
	v_exp_f32_e32 v52, v52
	v_exp_f32_e32 v53, v53
	v_cvt_pk_bf16_f32 v61, v50, v51
	v_add_u32_e32 v50, 0x90, v148
	v_add_f32_e32 v52, 1.0, v52
	v_add_f32_e32 v53, 1.0, v53
	v_rcp_f32_e32 v52, v52
	v_rcp_f32_e32 v53, v53
	v_mad_i64_i32 v[50:51], s[14:15], v50, s3, v[140:141]
	v_lshl_add_u64 v[50:51], v[50:51], 0, v[142:143]
	v_pk_mul_f32 v[46:47], v[46:47], v[52:53]
	global_store_dwordx4 v[66:67], v[58:61], off
	v_pk_mul_f32 v[42:43], v[46:47], v[42:43]
	s_nop 0
	v_cvt_pk_bf16_f32 v42, v42, v43
	v_mul_f32_e32 v43, 0xbfb8aa3b, v48
	v_exp_f32_e32 v43, v43
	s_nop 0
	v_add_f32_e32 v43, 1.0, v43
	v_rcp_f32_e32 v46, v43
	v_mul_f32_e32 v43, 0xbfb8aa3b, v49
	v_exp_f32_e32 v43, v43
	s_nop 0
	v_add_f32_e32 v43, 1.0, v43
	v_rcp_f32_e32 v47, v43
	s_nop 0
	v_pk_mul_f32 v[46:47], v[48:49], v[46:47]
	s_nop 0
	v_pk_mul_f32 v[44:45], v[46:47], v[44:45]
	s_nop 0
	v_cvt_pk_bf16_f32 v43, v44, v45
	v_mul_f32_e32 v44, 0xbfb8aa3b, v38
	v_mul_f32_e32 v45, 0xbfb8aa3b, v39
	v_exp_f32_e32 v44, v44
	v_exp_f32_e32 v45, v45
	v_add_f32_e32 v44, 1.0, v44
	v_add_f32_e32 v45, 1.0, v45
	v_rcp_f32_e32 v44, v44
	v_rcp_f32_e32 v45, v45
	s_nop 0
	v_pk_mul_f32 v[38:39], v[38:39], v[44:45]
	s_nop 0
	v_pk_mul_f32 v[34:35], v[38:39], v[34:35]
	s_nop 0
	v_cvt_pk_bf16_f32 v44, v34, v35
	v_mul_f32_e32 v34, 0xbfb8aa3b, v40
	v_mul_f32_e32 v35, 0xbfb8aa3b, v41
	v_exp_f32_e32 v34, v34
	v_exp_f32_e32 v35, v35
	v_add_f32_e32 v34, 1.0, v34
	v_add_f32_e32 v35, 1.0, v35
	v_rcp_f32_e32 v34, v34
	v_rcp_f32_e32 v35, v35
	s_nop 0
	v_pk_mul_f32 v[34:35], v[40:41], v[34:35]
	s_nop 0
	v_pk_mul_f32 v[34:35], v[34:35], v[36:37]
	v_mul_f32_e32 v36, 0xbfb8aa3b, v30
	v_mul_f32_e32 v37, 0xbfb8aa3b, v31
	v_exp_f32_e32 v36, v36
	v_exp_f32_e32 v37, v37
	v_cvt_pk_bf16_f32 v45, v34, v35
	v_add_u32_e32 v34, 0xa0, v148
	v_add_f32_e32 v36, 1.0, v36
	v_add_f32_e32 v37, 1.0, v37
	v_rcp_f32_e32 v36, v36
	v_rcp_f32_e32 v37, v37
	v_mad_i64_i32 v[34:35], s[14:15], v34, s3, v[140:141]
	v_lshl_add_u64 v[34:35], v[34:35], 0, v[142:143]
	v_pk_mul_f32 v[30:31], v[30:31], v[36:37]
	global_store_dwordx4 v[50:51], v[42:45], off
	v_pk_mul_f32 v[26:27], v[30:31], v[26:27]
	s_nop 0
	v_cvt_pk_bf16_f32 v26, v26, v27
	v_mul_f32_e32 v27, 0xbfb8aa3b, v32
	v_exp_f32_e32 v27, v27
	s_nop 0
	v_add_f32_e32 v27, 1.0, v27
	v_rcp_f32_e32 v30, v27
	v_mul_f32_e32 v27, 0xbfb8aa3b, v33
	v_exp_f32_e32 v27, v27
	s_nop 0
	v_add_f32_e32 v27, 1.0, v27
	v_rcp_f32_e32 v31, v27
	s_nop 0
	v_pk_mul_f32 v[30:31], v[32:33], v[30:31]
	s_nop 0
	v_pk_mul_f32 v[28:29], v[30:31], v[28:29]
	s_nop 0
	v_cvt_pk_bf16_f32 v27, v28, v29
	v_mul_f32_e32 v28, 0xbfb8aa3b, v22
	v_mul_f32_e32 v29, 0xbfb8aa3b, v23
	v_exp_f32_e32 v28, v28
	v_exp_f32_e32 v29, v29
	v_add_f32_e32 v28, 1.0, v28
	v_add_f32_e32 v29, 1.0, v29
	v_rcp_f32_e32 v28, v28
	v_rcp_f32_e32 v29, v29
	s_nop 0
	v_pk_mul_f32 v[22:23], v[22:23], v[28:29]
	s_nop 0
	v_pk_mul_f32 v[18:19], v[22:23], v[18:19]
	s_nop 0
	v_cvt_pk_bf16_f32 v28, v18, v19
	v_mul_f32_e32 v18, 0xbfb8aa3b, v24
	v_mul_f32_e32 v19, 0xbfb8aa3b, v25
	v_exp_f32_e32 v18, v18
	v_exp_f32_e32 v19, v19
	v_add_f32_e32 v18, 1.0, v18
	v_add_f32_e32 v19, 1.0, v19
	v_rcp_f32_e32 v18, v18
	v_rcp_f32_e32 v19, v19
	s_nop 0
	v_pk_mul_f32 v[18:19], v[24:25], v[18:19]
	s_nop 0
	v_pk_mul_f32 v[18:19], v[18:19], v[20:21]
	v_mul_f32_e32 v20, 0xbfb8aa3b, v14
	v_mul_f32_e32 v21, 0xbfb8aa3b, v15
	v_exp_f32_e32 v20, v20
	v_exp_f32_e32 v21, v21
	v_cvt_pk_bf16_f32 v29, v18, v19
	v_add_u32_e32 v18, 0xb0, v148
	v_add_f32_e32 v20, 1.0, v20
	v_add_f32_e32 v21, 1.0, v21
	v_rcp_f32_e32 v20, v20
	v_rcp_f32_e32 v21, v21
	v_mad_i64_i32 v[18:19], s[14:15], v18, s3, v[140:141]
	v_lshl_add_u64 v[18:19], v[18:19], 0, v[142:143]
	v_pk_mul_f32 v[14:15], v[14:15], v[20:21]
	s_mov_b64 s[14:15], -1
	v_pk_mul_f32 v[10:11], v[14:15], v[10:11]
	global_store_dwordx4 v[34:35], v[26:29], off
	v_cvt_pk_bf16_f32 v10, v10, v11
	v_mul_f32_e32 v11, 0xbfb8aa3b, v16
	v_exp_f32_e32 v11, v11
	s_nop 0
	v_add_f32_e32 v11, 1.0, v11
	v_rcp_f32_e32 v14, v11
	v_mul_f32_e32 v11, 0xbfb8aa3b, v17
	v_exp_f32_e32 v11, v11
	s_nop 0
	v_add_f32_e32 v11, 1.0, v11
	v_rcp_f32_e32 v15, v11
	s_nop 0
	v_pk_mul_f32 v[14:15], v[16:17], v[14:15]
	s_nop 0
	v_pk_mul_f32 v[12:13], v[14:15], v[12:13]
	s_nop 0
	v_cvt_pk_bf16_f32 v11, v12, v13
	v_mul_f32_e32 v12, 0xbfb8aa3b, v6
	v_mul_f32_e32 v13, 0xbfb8aa3b, v7
	v_exp_f32_e32 v12, v12
	v_exp_f32_e32 v13, v13
	v_add_f32_e32 v12, 1.0, v12
	v_add_f32_e32 v13, 1.0, v13
	v_rcp_f32_e32 v12, v12
	v_rcp_f32_e32 v13, v13
	s_nop 0
	v_pk_mul_f32 v[6:7], v[6:7], v[12:13]
	s_nop 0
	v_pk_mul_f32 v[2:3], v[6:7], v[2:3]
	s_nop 0
	v_cvt_pk_bf16_f32 v12, v2, v3
	v_mul_f32_e32 v2, 0xbfb8aa3b, v8
	v_mul_f32_e32 v3, 0xbfb8aa3b, v9
	v_exp_f32_e32 v2, v2
	v_exp_f32_e32 v3, v3
	v_add_f32_e32 v2, 1.0, v2
	v_add_f32_e32 v3, 1.0, v3
	v_rcp_f32_e32 v2, v2
	v_rcp_f32_e32 v3, v3
	s_nop 0
	v_pk_mul_f32 v[2:3], v[8:9], v[2:3]
	s_nop 0
	v_pk_mul_f32 v[2:3], v[2:3], v[4:5]
	s_nop 0
	v_cvt_pk_bf16_f32 v13, v2, v3
	global_store_dwordx4 v[18:19], v[10:13], off
	s_cbranch_vccnz .LBB0_322
	s_and_b64 vcc, exec, s[4:5]
	s_cbranch_vccnz .LBB0_321
	s_barrier
	s_branch .LBB0_321
